# differential attention K/V tile loop unrolled by two: LDS double-buffer offsets as immediates / loop-invariant address registers, even half without has-next logic, ones vector hoisted
# speedup vs baseline: 1.0049x; 1.0049x over previous
; template <bool DIFF>
; __device__ __forceinline__ void attn_unit(CA& A, int l, int b, int hh, int qb, LAS unsigned char* lds, float lam, float lam_init) {
;     constexpr int DQK = DIFF ? 32 : 64, NS = DQK / 16, QROWS = DIFF ? 128 : 256;
;     const int tid = otid(), lane = tid & 63, wid = __builtin_amdgcn_readfirstlane(tid >> 6), r32 = lane & 31, hi = lane >> 5;
;     const int q0 = qb * QROWS, wq = DIFF ? (wid & 3) * 32 : wid * 32, strm = DIFF ? (wid >> 2) : 0;
;     const bf16_t* Zb = (const bf16_t*)(A.ws + WS_Z) + (size_t)b * SEQ * ZC;
;     bf16_t* MIX = (bf16_t*)(A.ws + WS_MIX);
;     const int qcol = DIFF ? (DIFF_Q0 + hh * 64 + strm * 32) : (FOX_Q0 + hh * 64);
;     const int kcol = DIFF ? (DIFF_K0 + hh * 64) : (FOX_K0 + hh * 64);
;     const int vcol = DIFF ? (DIFF_V0 + hh * 64) : (FOX_V0 + hh * 64);
;     const float* gq = DIFF ? A.diff_qk_g + l * 64 : A.fox_qk_g + l * 128;
;     const float* gk = gq + DQK;
;     const int skey = tid >> 3, sch = tid & 7;
;     const bf16_t* kp = Zb + (size_t)skey * ZC + kcol + 8 * sch;
;     const bf16_t* vp = Zb + (size_t)lane * ZC + vcol + 8 * wid;
;     const float* ncp = (const float*)(A.ws + WS_NEGC) + (size_t)(b * 4 + hh) * SEQ;
;     const int NT = (q0 + QROWS) / 64;
;     v4u kraw, vraw; float ncv = 0.f;
;     v4u qraw[NS];
;     {
;         const bf16_t* qp = Zb + (size_t)(q0 + wq + r32) * ZC + qcol + 8 * hi;
; #pragma unroll
;         for (int s = 0; s < NS; ++s) qraw[s] = *(const v4u*)(qp + 16 * s);
;     }
;     { const int t0_ = DIFF ? 0 : NT - 1; kraw = *(const v4u*)(kp + (size_t)t0_ * 64 * ZC); vraw = *(const v4u*)(vp + (size_t)t0_ * 64 * ZC); }
;     const float gkl = gk[lane & (DQK - 1)];
;     bf16x8 qf[NS]; float qn2 = 0.f;
; #pragma unroll
;     for (int s = 0; s < NS; ++s) { qf[s] = __builtin_bit_cast(bf16x8, qraw[s]);
; #pragma unroll
;         for (int i = 0; i < 4; ++i) qn2 += bflo(qraw[s][i]) * bflo(qraw[s][i]) + bfhi(qraw[s][i]) * bfhi(qraw[s][i]); }
;     qn2 += shx(qn2, 32);
;     float qkb;
;     {
;         float gm = fabsf(gkl);
; #pragma unroll
;         for (int o_ = 1; o_ < 64; o_ <<= 1) gm = fmaxf(gm, shx(gm, o_));
;         qkb = sqrtf(qn2) * sqrtf((float)DQK) * gm * 1.02f;
;     }
; __device__ __forceinline__ void mix_phase(CA& A0, int l, LAS unsigned char* lds) {
;     ...
;         if (ait >= 0) {
;             const int level = 15 - ait / 48, r = ait % 48, grp = r / 16, bh = r % 16;
.LBB0_738:
	s_andn2_b64 vcc, exec, s[4:5]
	s_cbranch_vccnz .LBB0_658
	s_and_b32 s4, s20, 0xffff
	s_mul_i32 s4, s4, 0xaaab
	s_lshr_b32 s12, s4, 21
	s_mul_i32 s4, s12, 48
	s_sub_i32 s4, s20, s4
	s_sub_i32 s14, 15, s12
	s_and_b32 s13, s4, 0xffff
	s_cmp_gt_u32 s13, 15
	s_mov_b64 s[4:5], -1
	s_cbranch_scc0 .LBB0_756
	v_mov_b32_e32 v1, v179
	s_load_dwordx2 s[6:7], s[34:35], 0xc8
	s_load_dwordx2 s[10:11], s[34:35], 0x58
	v_readfirstlane_b32 s17, v1
	s_bfe_u32 s16, s13, 0x20002
	s_and_b32 s4, s13, 48
	s_ashr_i32 s27, s17, 6
	s_lshl_b32 s5, s14, 8
	s_cmp_eq_u32 s4, 16
	s_cselect_b32 s29, 0x80, 0
	s_lshl_b32 s18, s27, 5
	s_or_b32 s19, s29, s5
	s_and_b32 s20, s18, 0x60
	s_ashr_i32 s24, s17, 8
	s_mul_i32 s30, s16, 0x1400000
	s_waitcnt lgkmcnt(0)
	s_add_u32 s4, s6, s30
	s_addc_u32 s5, s7, 0
	s_add_u32 s4, s4, 0x9500000
	s_addc_u32 s5, s5, 0
	s_lshl_b32 s8, s13, 6
	s_and_b32 s15, s8, 0xc0
	s_lshl_b32 s8, s88, 6
	s_lshl_b32 s37, s24, 5
	s_ashr_i32 s9, s8, 31
	s_add_i32 s38, s37, s15
	s_lshl_b64 s[8:9], s[8:9], 2
	v_and_b32_e32 v137, 31, v1
	s_add_u32 s10, s10, s8
	s_addc_u32 s11, s11, s9
	v_lshlrev_b32_e32 v4, 2, v137
	global_load_dword v10, v4, s[10:11] offset:128
	s_or_b32 s25, s20, s19
	v_or_b32_e32 v138, s25, v137
	v_mul_i32_i24_e32 v2, 0xa00, v138
	v_mov_b32_e32 v3, v0
	v_bfe_u32 v14, v1, 5, 1
	v_lshl_add_u64 v[2:3], v[2:3], 1, s[4:5]
	s_ashr_i32 s39, s38, 31
	v_lshl_add_u64 v[2:3], s[38:39], 1, v[2:3]
	v_lshlrev_b32_e32 v130, 4, v14
	v_mov_b32_e32 v131, v0
	v_lshl_add_u64 v[2:3], v[2:3], 0, v[130:131]
	global_load_dwordx4 v[112:115], v[2:3], off
	global_load_dwordx4 v[116:119], v[2:3], off offset:32
	v_and_b32_e32 v16, 63, v1
	v_mul_u32_u24_e32 v4, 0xa00, v16
	v_mov_b32_e32 v5, v0
	v_ashrrev_i32_e32 v17, 3, v1
	v_lshlrev_b32_e32 v4, 1, v4
	v_mov_b64_e32 v[6:7], s[4:5]
	v_lshl_add_u64 v[8:9], s[4:5], 0, v[4:5]
	v_mad_i64_i32 v[6:7], s[4:5], v17, s93, v[6:7]
	v_readlane_b32 s38, v237, 58
	v_lshlrev_b32_e32 v1, 4, v1
	v_readlane_b32 s39, v237, 59
	s_lshl_b32 s38, s15, 1
	s_lshl_b32 s4, s27, 3
	v_mov_b32_e32 v3, v0
	v_and_b32_e32 v2, 0x70, v1
	v_lshl_add_u64 v[6:7], v[6:7], 0, s[38:39]
	s_ashr_i32 s5, s4, 31
	v_lshl_add_u64 v[8:9], v[8:9], 0, s[38:39]
	v_lshl_add_u64 v[6:7], v[6:7], 0, v[2:3]
	s_lshl_b64 s[10:11], s[4:5], 1
	v_lshl_add_u64 v[8:9], v[8:9], 0, s[10:11]
	global_load_dwordx4 v[120:123], v[6:7], off offset:512
	global_load_dwordx4 v[124:127], v[8:9], off offset:1024
	v_mov_b32_e32 v15, v179
	v_mov_b32_e32 v11, v179
	v_mov_b32_e32 v12, v179
	v_lshlrev_b32_e32 v1, 2, v11
	v_bitop3_b32 v1, v1, 4, v220 bitop3:0x6c
	s_mov_b32 s4, 0xf800000
	v_lshlrev_b32_e32 v3, 2, v12
	v_bitop3_b32 v3, v3, 8, v220 bitop3:0x6c
	s_mulk_i32 s27, 0x440
	s_add_i32 s28, s19, 0x80
	v_lshlrev_b32_e32 v131, 2, v14
	s_mov_b32 s26, 63
	s_mov_b32 s31, 0
	v_mul_u32_u24_e32 v142, 0x90, v137
	v_mul_u32_u24_e32 v145, 0x88, v137
	s_waitcnt vmcnt(4)
	v_and_b32_e32 v6, 0x7fffffff, v10
	ds_bpermute_b32 v1, v1, v6
	v_max_f32_e64 v12, |v10|, |v10|
	s_waitcnt lgkmcnt(0)
	v_max_f32_e32 v1, v1, v1
	v_max_f32_e32 v1, v12, v1
	ds_bpermute_b32 v3, v3, v1
	s_waitcnt vmcnt(3)
	v_and_b32_e32 v19, 0xffff0000, v112
	v_and_b32_e32 v21, 0xffff0000, v113
	s_waitcnt lgkmcnt(0)
	v_max_f32_e32 v3, v3, v3
	v_max_f32_e32 v1, v1, v3
	v_mov_b32_e32 v3, v179
	v_lshlrev_b32_e32 v18, 16, v112
	v_lshlrev_b32_e32 v3, 2, v3
	v_bitop3_b32 v3, v3, 16, v220 bitop3:0x6c
	ds_bpermute_b32 v3, v3, v1
	v_lshlrev_b32_e32 v20, 16, v113
	v_and_b32_e32 v9, 0xffff0000, v115
	v_and_b32_e32 v8, 0xffff0000, v114
	v_mul_f32_e32 v19, v19, v19
	s_waitcnt lgkmcnt(0)
	v_max_f32_e32 v3, v3, v3
	v_max_f32_e32 v1, v1, v3
	v_mov_b32_e32 v3, v179
	v_mul_f32_e32 v21, v21, v21
	v_lshlrev_b32_e32 v3, 2, v3
	v_bitop3_b32 v3, v3, 32, v220 bitop3:0x6c
	ds_bpermute_b32 v3, v3, v1
	v_lshlrev_b32_e32 v7, 16, v115
	v_lshlrev_b32_e32 v6, 16, v114
	v_pk_mul_f32 v[8:9], v[8:9], v[8:9]
	v_fmac_f32_e32 v19, v18, v18
	v_fmac_f32_e32 v21, v20, v20
	v_pk_fma_f32 v[6:7], v[6:7], v[6:7], v[8:9]
	v_add_f32_e32 v8, v19, v21
	s_waitcnt vmcnt(2)
	v_and_b32_e32 v13, 0xffff0000, v117
	v_add_f32_e32 v6, v6, v8
	v_and_b32_e32 v12, 0xffff0000, v116
	s_waitcnt lgkmcnt(0)
	v_max_f32_e32 v3, v3, v3
	v_lshlrev_b32_e32 v11, 16, v117
	v_lshlrev_b32_e32 v10, 16, v116
	v_add_f32_e32 v8, v7, v6
	v_pk_mul_f32 v[6:7], v[12:13], v[12:13]
	v_max_f32_e32 v1, v1, v3
	v_mov_b32_e32 v3, v179
	v_pk_fma_f32 v[6:7], v[10:11], v[10:11], v[6:7]
	v_and_b32_e32 v9, 0xffff0000, v119
	v_add_f32_e32 v6, v6, v8
	v_and_b32_e32 v8, 0xffff0000, v118
	v_lshlrev_b32_e32 v3, 2, v3
	v_add_f32_e32 v10, v7, v6
	v_lshlrev_b32_e32 v7, 16, v119
	v_lshlrev_b32_e32 v6, 16, v118
	v_pk_mul_f32 v[8:9], v[8:9], v[8:9]
	v_bitop3_b32 v3, v3, 64, v220 bitop3:0x6c
	v_pk_fma_f32 v[6:7], v[6:7], v[6:7], v[8:9]
	ds_bpermute_b32 v3, v3, v1
	v_add_f32_e32 v6, v6, v10
	v_add_f32_e32 v6, v7, v6
	v_lshlrev_b32_e32 v7, 2, v15
	v_bitop3_b32 v7, v7, s33, v220 bitop3:0x6c
	ds_bpermute_b32 v7, v7, v6
	s_waitcnt lgkmcnt(1)
	v_max_f32_e32 v3, v3, v3
	v_max_f32_e32 v1, v1, v3
	v_mov_b32_e32 v3, v179
	s_waitcnt lgkmcnt(0)
	v_add_f32_e32 v6, v6, v7
	v_lshlrev_b32_e32 v3, 2, v3
	v_bitop3_b32 v3, v3, s33, v220 bitop3:0x6c
	ds_bpermute_b32 v3, v3, v1
	v_mul_f32_e32 v7, 0x4f800000, v6
	v_cmp_gt_f32_e32 vcc, s4, v6
	v_lshlrev_b32_e32 v8, 3, v14
	v_mov_b32_e32 v14, v0
	v_cndmask_b32_e32 v6, v6, v7, vcc
	v_sqrt_f32_e32 v7, v6
	s_waitcnt lgkmcnt(0)
; #define LAS __attribute__((address_space(3)))
; template <bool DIFF>
; __device__ __forceinline__ void attn_unit(CA& A, int l, int b, int hh, int qb, LAS unsigned char* lds, float lam, float lam_init) {
;     ...
;     float ncq = 0.f;
;     if (!DIFF) { if (tid < 64) ncv = ncp[(NT - 1) * 64 + tid]; ncq = ncp[q0 + wq + r32]; }
;     ATT_WRITE(0);
;     __syncthreads();
;     f32x16 o[2], ol; float m_ref = 0.f;
; #pragma unroll
;     for (int r = 0; r < 16; ++r) { o[0][r] = 0.f; o[1][r] = 0.f; ol[r] = 0.f; }
;     f32x16 negm;
; #pragma unroll
;     for (int r = 0; r < 16; ++r) negm[r] = 0.f;
;     const bf16x8 ones = {0x3F80, 0x3F80, 0x3F80, 0x3F80, 0x3F80, 0x3F80, 0x3F80, 0x3F80};
;     const int qfirst = q0 + wq, qlast = qfirst + 31, qmine = qfirst + r32;
;     const int koff = DIFF ? strm * 32 : 0;
;     if (DIFF) {
;         m_ref = qkb;
; #pragma unroll
;         for (int r = 0; r < 16; ++r) negm[r] = -qkb;
;     } else {
;         m_ref = qkb + ncq;
;     }
;     volatile LAS int* votes = (volatile LAS int*)(lds + LDS_MAIN + 64);
;     bool first = true;
	v_max_f32_e32 v3, v3, v3
	v_max_f32_e32 v1, v1, v3
	v_mov_b32_e32 v15, v0
	v_add_u32_e32 v3, -1, v7
	v_fma_f32 v9, -v3, v7, v6
	v_cmp_ge_f32_e64 s[4:5], 0, v9
	v_add_u32_e32 v9, 1, v7
	v_add_u32_e32 v141, 0, v8
	v_cndmask_b32_e64 v3, v7, v3, s[4:5]
	v_fma_f32 v7, -v9, v7, v6
	v_cmp_lt_f32_e64 s[4:5], 0, v7
	v_mov_b32_e32 v10, v0
	v_mov_b32_e32 v11, v0
	v_cndmask_b32_e64 v3, v3, v9, s[4:5]
	s_add_i32 s4, s27, 0
	v_lshl_add_u32 v140, v16, 1, s4
	s_and_b32 s4, s13, 3
	s_lshl_b32 s4, s4, 7
	v_mul_f32_e32 v7, 0x37800000, v3
	s_lshr_b32 s27, s28, 6
	s_or_b32 s28, s25, 31
	s_or_b32 s38, s30, s4
	v_cndmask_b32_e32 v3, v3, v7, vcc
	v_cmp_class_f32_e32 vcc, v6, v219
	s_movk_i32 s5, 0x90
	s_add_u32 s4, s38, s10
	v_cndmask_b32_e32 v3, v3, v6, vcc
	v_mul_lo_u32 v6, v17, s5
	v_mad_u32_u24 v144, v137, s5, v224
	s_addc_u32 s5, 0, s11
	s_add_u32 s4, s6, s4
	s_addc_u32 s5, s7, s5
	v_lshl_add_u64 v[4:5], s[4:5], 0, v[4:5]
	s_mov_b64 s[4:5], 0x9550400
	v_lshl_add_u64 v[132:133], v[4:5], 0, s[4:5]
	s_mov_b32 s5, s39
	v_writelane_b32 v237, s4, 58
	v_mov_b64_e32 v[4:5], s[38:39]
	v_mul_f32_e32 v3, 0x40b504f3, v3
	v_writelane_b32 v237, s5, 59
	v_mad_i64_i32 v[4:5], s[4:5], v17, s93, v[4:5]
	v_or_b32_e32 v4, v4, v2
	v_add3_u32 v139, 0, v6, v2
	v_mul_f32_e32 v1, v3, v1
	v_lshl_add_u64 v[2:3], s[6:7], 0, v[4:5]
	s_mov_b64 s[4:5], 0x9550200
	v_lshl_add_u64 v[134:135], v[2:3], 0, s[4:5]
	s_lshl_b32 s4, s12, 8
	v_mul_f32_e32 v48, 0xbf828f5c, v1
	v_or_b32_e32 v1, s37, v8
	s_sub_i32 s4, s29, s4
	v_lshlrev_b32_e32 v143, 1, v1
	s_addk_i32 s4, 0xf80
	v_mov_b32_e32 v1, v0
	v_mov_b32_e32 v2, v0
	v_mov_b32_e32 v3, v0
	v_mov_b32_e32 v4, v0
	v_mov_b32_e32 v5, v0
	v_mov_b32_e32 v6, v0
	v_mov_b32_e32 v7, v0
	v_mov_b32_e32 v8, v0
	v_mov_b32_e32 v9, v0
	v_mov_b32_e32 v12, v0
	v_mov_b32_e32 v13, v0
	v_mov_b64_e32 v[46:47], v[14:15]
	v_mov_b64_e32 v[30:31], v[14:15]
	v_mov_b64_e32 v[78:79], v[14:15]
	v_mov_b32_e32 v49, v48
	v_mov_b32_e32 v50, v48
	v_mov_b32_e32 v51, v48
	v_mov_b32_e32 v52, v48
	v_mov_b32_e32 v53, v48
	v_mov_b32_e32 v54, v48
	v_mov_b32_e32 v55, v48
	v_mov_b32_e32 v56, v48
	v_mov_b32_e32 v57, v48
	v_mov_b32_e32 v58, v48
	v_mov_b32_e32 v59, v48
	v_mov_b32_e32 v60, v48
	v_mov_b32_e32 v61, v48
	v_mov_b32_e32 v62, v48
	v_mov_b32_e32 v63, v48
	s_lshr_b32 s10, s4, 6
	v_mov_b64_e32 v[44:45], v[12:13]
	v_mov_b64_e32 v[42:43], v[10:11]
	v_mov_b64_e32 v[40:41], v[8:9]
	v_mov_b64_e32 v[38:39], v[6:7]
	v_mov_b64_e32 v[36:37], v[4:5]
	v_mov_b64_e32 v[34:35], v[2:3]
	v_mov_b64_e32 v[32:33], v[0:1]
	v_mov_b64_e32 v[28:29], v[12:13]
	v_mov_b64_e32 v[26:27], v[10:11]
	v_mov_b64_e32 v[24:25], v[8:9]
	v_mov_b64_e32 v[22:23], v[6:7]
	v_mov_b64_e32 v[20:21], v[4:5]
	v_mov_b64_e32 v[18:19], v[2:3]
	v_mov_b64_e32 v[16:17], v[0:1]
	v_mov_b64_e32 v[76:77], v[12:13]
	v_mov_b64_e32 v[74:75], v[10:11]
	v_mov_b64_e32 v[72:73], v[8:9]
	v_mov_b64_e32 v[70:71], v[6:7]
	v_mov_b64_e32 v[68:69], v[4:5]
	v_mov_b64_e32 v[66:67], v[2:3]
	v_mov_b64_e32 v[64:65], v[0:1]
	s_waitcnt vmcnt(1)
	ds_write_b128 v139, v[120:123]
	s_waitcnt vmcnt(0)
	ds_write_b16 v140, v124 offset:18432
	ds_write_b16_d16_hi v140, v124 offset:18568
	ds_write_b16 v140, v125 offset:18704
	ds_write_b16_d16_hi v140, v125 offset:18840
	ds_write_b16 v140, v126 offset:18976
	ds_write_b16_d16_hi v140, v126 offset:19112
	ds_write_b16 v140, v127 offset:19248
	ds_write_b16_d16_hi v140, v127 offset:19384
	s_waitcnt lgkmcnt(0)
	s_barrier
	v_add_u32_e32 v200, v142, v143
	v_add_u32_e32 v201, v144, v143
	v_add_u32_e32 v214, v141, v145
	v_mov_b32_e32 v204, s36
	v_mov_b32_e32 v205, s36
	v_mov_b32_e32 v206, s36
	v_mov_b32_e32 v207, s36
	v_add_u32_e32 v202, 0x4800, v214
	v_add_u32_e32 v203, 0x5800, v214
	v_add_u32_e32 v212, 0x6a00, v214
	v_add_u32_e32 v213, 0x7a00, v214
; #define LAS __attribute__((address_space(3)))
; __device__ __forceinline__ int crow(int r, int hi) { return (r & 3) + 8 * (r >> 2) + 4 * hi; }
; #define ATT_LOAD(t) do { kraw = *(const v4u*)(kp + (size_t)(t) * 64 * ZC); vraw = *(const v4u*)(vp + (size_t)(t) * 64 * ZC); \
;         if (!DIFF && tid < 64) ncv = ncp[(t) * 64 + tid]; } while (0)
; template <bool DIFF>
; __device__ __forceinline__ void attn_unit(CA& A, int l, int b, int hh, int qb, LAS unsigned char* lds, float lam, float lam_init) {
;     ...
;     for (int tt = 0; ; ++tt) {
;         const int t = DIFF ? tt : NT - 1 - tt;
;         const bool has_next = tt + 1 < NT;
;         const int buf = tt & 1, key0 = t * 64;
;         float nc_hi = 0.f;
;         if (has_next) { ATT_LOAD(DIFF ? t + 1 : t - 1); if (!DIFF) nc_hi = ncp[key0 - 1]; }
;         if (key0 <= qlast) {
;             const LAS unsigned char* Kb = lds + AL_KS + buf * AL_KSZ;
;             const LAS unsigned char* Vb = lds + AL_VT + buf * AL_VSZ;
;             f32x16 p[2];
; #pragma unroll
;             for (int kt = 0; kt < 2; ++kt) {
;                 if (!DIFF) {
;                     const LAS float* nc = (const LAS float*)(lds + AL_NC + buf * 512) + 32 * kt + 4 * hi;
; #pragma unroll
;                     for (int g = 0; g < 4; ++g) { const f32x4 c4 = *(const LAS f32x4*)(nc + 8 * g); p[kt][4 * g] = c4[0]; p[kt][4 * g + 1] = c4[1]; p[kt][4 * g + 2] = c4[2]; p[kt][4 * g + 3] = c4[3]; }
;                 }
; #pragma unroll
;                 for (int s = 0; s < NS; ++s) {
;                     const bf16x8 a = *(const LAS bf16x8*)(Kb + (32 * kt + r32) * 144 + (koff + 16 * s + 8 * hi) * 2);
;                     if (DIFF && s == 0) p[kt] = __builtin_amdgcn_mfma_f32_32x32x16_bf16(a, qf[s], negm, 0, 0, 0);
;                     else p[kt] = __builtin_amdgcn_mfma_f32_32x32x16_bf16(a, qf[s], p[kt], 0, 0, 0);
;                 }
;             }
;             if (!DIFF) {
; #pragma unroll
;                 for (int kt = 0; kt < 2; ++kt)
; #pragma unroll
;                     for (int r = 0; r < 16; ++r) p[kt][r] -= m_ref;
;             }
;             if (key0 + 63 > qfirst) {
; #pragma unroll
;                 for (int kt = 0; kt < 2; ++kt)
; #pragma unroll
;                     for (int r = 0; r < 16; ++r) if (key0 + 32 * kt + crow(r, hi) > qmine) p[kt][r] = -1e30f;
;             }
.LBB0_741:
	global_load_dwordx4 v[120:123], v[134:135], off
	global_load_dwordx4 v[124:127], v[132:133], off
	s_sub_i32 s30, s26, 63
	s_cmp_gt_u32 s30, s28
	s_cbranch_scc1 .Lmy_de_w
	ds_read_b128 v[148:151], v200
	ds_read_b128 v[152:155], v201
	ds_read_b128 v[156:159], v200 offset:32
	ds_read_b128 v[160:163], v201 offset:32
	s_waitcnt lgkmcnt(2)
	v_mfma_f32_32x32x16_bf16 v[96:111], v[148:151], v[112:115], v[48:63]
	v_mfma_f32_32x32x16_bf16 v[80:95], v[152:155], v[112:115], v[48:63]
	s_waitcnt lgkmcnt(0)
	v_mfma_f32_32x32x16_bf16 v[96:111], v[156:159], v[116:119], v[96:111]
	v_mfma_f32_32x32x16_bf16 v[80:95], v[160:163], v[116:119], v[80:95]
	ds_read2_b64 v[164:167], v202 offset0:0 offset1:2
	ds_read2_b64 v[168:171], v203 offset0:32 offset1:34
	ds_read2_b64 v[172:175], v202 offset0:4 offset1:6
	ds_read2_b64 v[180:183], v203 offset0:36 offset1:38
	ds_read2_b64 v[184:187], v202 offset0:8 offset1:10
	ds_read2_b64 v[188:191], v203 offset0:40 offset1:42
	ds_read2_b64 v[192:195], v202 offset0:12 offset1:14
	ds_read2_b64 v[196:199], v203 offset0:44 offset1:46
	s_cmp_le_u32 s26, s25
	s_nop 1
	s_cbranch_scc1 .Lmy_d0_pv
	v_add_u32_e32 v1, s26, v131
	v_subrev_u32_e32 v2, 63, v1
	v_cmp_gt_u32_e32 vcc, v2, v138
	s_nop 1
	v_cndmask_b32_e32 v3, v96, v225, vcc
	v_cmp_lt_u32_e32 vcc, v2, v138
	v_subrev_u32_e32 v2, 61, v1
	s_nop 0
	v_cndmask_b32_e32 v96, v3, v96, vcc
	v_cndmask_b32_e32 v97, v225, v97, vcc
	v_cmp_le_u32_e32 vcc, v2, v138
	v_subrev_u32_e32 v2, 60, v1
	s_nop 0
	v_cndmask_b32_e32 v98, v225, v98, vcc
	v_cmp_le_u32_e32 vcc, v2, v138
	v_subrev_u32_e32 v2, 55, v1
	s_nop 0
	v_cndmask_b32_e32 v99, v225, v99, vcc
	v_cmp_le_u32_e32 vcc, v2, v138
	v_subrev_u32_e32 v2, 54, v1
	s_nop 0
	v_cndmask_b32_e32 v100, v225, v100, vcc
	v_cmp_le_u32_e32 vcc, v2, v138
	v_subrev_u32_e32 v2, 53, v1
	s_nop 0
	v_cndmask_b32_e32 v101, v225, v101, vcc
	v_cmp_le_u32_e32 vcc, v2, v138
	v_subrev_u32_e32 v2, 52, v1
	s_nop 0
	v_cndmask_b32_e32 v102, v225, v102, vcc
	v_cmp_le_u32_e32 vcc, v2, v138
	v_subrev_u32_e32 v2, 47, v1
	s_nop 0
	v_cndmask_b32_e32 v103, v225, v103, vcc
	v_cmp_le_u32_e32 vcc, v2, v138
	v_subrev_u32_e32 v2, 46, v1
	s_nop 0
	v_cndmask_b32_e32 v104, v225, v104, vcc
	v_cmp_le_u32_e32 vcc, v2, v138
	v_subrev_u32_e32 v2, 45, v1
	s_nop 0
	v_cndmask_b32_e32 v105, v225, v105, vcc
	v_cmp_le_u32_e32 vcc, v2, v138
	v_subrev_u32_e32 v2, 44, v1
	s_nop 0
	v_cndmask_b32_e32 v106, v225, v106, vcc
	v_cmp_le_u32_e32 vcc, v2, v138
	v_subrev_u32_e32 v2, 39, v1
	s_nop 0
	v_cndmask_b32_e32 v107, v225, v107, vcc
	v_cmp_le_u32_e32 vcc, v2, v138
	v_subrev_u32_e32 v2, 38, v1
	s_nop 0
	v_cndmask_b32_e32 v108, v225, v108, vcc
	v_cmp_le_u32_e32 vcc, v2, v138
	v_subrev_u32_e32 v2, 37, v1
	s_nop 0
	v_cndmask_b32_e32 v109, v225, v109, vcc
	v_cmp_le_u32_e32 vcc, v2, v138
	v_subrev_u32_e32 v2, 36, v1
	s_nop 0
	v_cndmask_b32_e32 v110, v225, v110, vcc
	v_cmp_le_u32_e32 vcc, v2, v138
	v_subrev_u32_e32 v2, 31, v1
	s_nop 0
	v_cndmask_b32_e32 v111, v225, v111, vcc
	v_cmp_le_u32_e32 vcc, v2, v138
	v_subrev_u32_e32 v2, 30, v1
	s_nop 0
	v_cndmask_b32_e32 v80, v225, v80, vcc
	v_cmp_le_u32_e32 vcc, v2, v138
	v_subrev_u32_e32 v2, 29, v1
	s_nop 0
	v_cndmask_b32_e32 v81, v225, v81, vcc
	v_cmp_le_u32_e32 vcc, v2, v138
	v_subrev_u32_e32 v2, 28, v1
	s_nop 0
	v_cndmask_b32_e32 v82, v225, v82, vcc
	v_cmp_le_u32_e32 vcc, v2, v138
	v_subrev_u32_e32 v2, 23, v1
	s_nop 0
	v_cndmask_b32_e32 v83, v225, v83, vcc
	v_cmp_le_u32_e32 vcc, v2, v138
	v_subrev_u32_e32 v2, 22, v1
	s_nop 0
	v_cndmask_b32_e32 v84, v225, v84, vcc
	v_cmp_le_u32_e32 vcc, v2, v138
	v_subrev_u32_e32 v2, 21, v1
	s_nop 0
	v_cndmask_b32_e32 v85, v225, v85, vcc
	v_cmp_le_u32_e32 vcc, v2, v138
	v_subrev_u32_e32 v2, 20, v1
	s_nop 0
	v_cndmask_b32_e32 v86, v225, v86, vcc
	v_cmp_le_u32_e32 vcc, v2, v138
	v_add_u32_e32 v2, -15, v1
	s_nop 0
	v_cndmask_b32_e32 v87, v225, v87, vcc
	v_cmp_le_u32_e32 vcc, v2, v138
	v_add_u32_e32 v2, -14, v1
	s_nop 0
	v_cndmask_b32_e32 v88, v225, v88, vcc
	v_cmp_le_u32_e32 vcc, v2, v138
	v_add_u32_e32 v2, -13, v1
	s_nop 0
	v_cndmask_b32_e32 v89, v225, v89, vcc
	v_cmp_le_u32_e32 vcc, v2, v138
	v_add_u32_e32 v2, -12, v1
	s_nop 0
	v_cndmask_b32_e32 v90, v225, v90, vcc
	v_cmp_le_u32_e32 vcc, v2, v138
	v_add_u32_e32 v2, -7, v1
	s_nop 0
	v_cndmask_b32_e32 v91, v225, v91, vcc
	v_cmp_le_u32_e32 vcc, v2, v138
	v_add_u32_e32 v2, -6, v1
	s_nop 0
	v_cndmask_b32_e32 v92, v225, v92, vcc
	v_cmp_le_u32_e32 vcc, v2, v138
	v_add_u32_e32 v2, -5, v1
	v_add_u32_e32 v1, -4, v1
	v_cndmask_b32_e32 v93, v225, v93, vcc
	v_cmp_le_u32_e32 vcc, v2, v138
	s_nop 1
	v_cndmask_b32_e32 v94, v225, v94, vcc
	v_cmp_le_u32_e32 vcc, v1, v138
	s_nop 1
	v_cndmask_b32_e32 v95, v225, v95, vcc

; #define LAS __attribute__((address_space(3)))
; __device__ __forceinline__ int crow(int r, int hi) { return (r & 3) + 8 * (r >> 2) + 4 * hi; }
; template <bool DIFF>
; __device__ __forceinline__ void attn_unit(CA& A, int l, int b, int hh, int qb, LAS unsigned char* lds, float lam, float lam_init) {
;     ...
;         if (key0 <= qlast) {
;             const LAS unsigned char* Kb = lds + AL_KS + buf * AL_KSZ;
;             const LAS unsigned char* Vb = lds + AL_VT + buf * AL_VSZ;
;             f32x16 p[2];
; #pragma unroll
;             for (int kt = 0; kt < 2; ++kt) {
;                 if (!DIFF) {
;                     const LAS float* nc = (const LAS float*)(lds + AL_NC + buf * 512) + 32 * kt + 4 * hi;
; #pragma unroll
;                     for (int g = 0; g < 4; ++g) { const f32x4 c4 = *(const LAS f32x4*)(nc + 8 * g); p[kt][4 * g] = c4[0]; p[kt][4 * g + 1] = c4[1]; p[kt][4 * g + 2] = c4[2]; p[kt][4 * g + 3] = c4[3]; }
;                 }
; #pragma unroll
;                 for (int s = 0; s < NS; ++s) {
;                     const bf16x8 a = *(const LAS bf16x8*)(Kb + (32 * kt + r32) * 144 + (koff + 16 * s + 8 * hi) * 2);
;                     if (DIFF && s == 0) p[kt] = __builtin_amdgcn_mfma_f32_32x32x16_bf16(a, qf[s], negm, 0, 0, 0);
;                     else p[kt] = __builtin_amdgcn_mfma_f32_32x32x16_bf16(a, qf[s], p[kt], 0, 0, 0);
;                 }
;             }
;             if (!DIFF) {
; #pragma unroll
;                 for (int kt = 0; kt < 2; ++kt)
; #pragma unroll
;                     for (int r = 0; r < 16; ++r) p[kt][r] -= m_ref;
;             }
;             if (key0 + 63 > qfirst) {
; #pragma unroll
;                 for (int kt = 0; kt < 2; ++kt)
; #pragma unroll
;                     for (int r = 0; r < 16; ++r) if (key0 + 32 * kt + crow(r, hi) > qmine) p[kt][r] = -1e30f;
;             }
.Lmy_de_w:
	s_waitcnt vmcnt(1)
	ds_write_b128 v139, v[120:123] offset:9216
	s_waitcnt vmcnt(0)
	ds_write_b16 v140, v124 offset:27136
	ds_write_b16_d16_hi v140, v124 offset:27272
	ds_write_b16 v140, v125 offset:27408
	ds_write_b16_d16_hi v140, v125 offset:27544
	ds_write_b16 v140, v126 offset:27680
	ds_write_b16_d16_hi v140, v126 offset:27816
	ds_write_b16 v140, v127 offset:27952
	ds_write_b16_d16_hi v140, v127 offset:28088
	s_add_i32 s26, s26, 64
	s_mov_b64 s[4:5], 0x50000
	v_lshl_add_u64 v[132:133], v[132:133], 0, s[4:5]
	v_lshl_add_u64 v[134:135], v[134:135], 0, s[4:5]
	s_add_i32 s31, s31, 1
	s_waitcnt lgkmcnt(0)
	s_barrier
	s_add_i32 s11, s31, 1
	s_cmp_lt_u32 s11, s27
	s_cselect_b64 s[4:5], -1, 0
	s_cbranch_scc0 .Lmy_do_nold
	global_load_dwordx4 v[120:123], v[134:135], off
	global_load_dwordx4 v[124:127], v[132:133], off
.Lmy_do_nold:
	s_sub_i32 s30, s26, 63
	s_cmp_gt_u32 s30, s28
	s_cbranch_scc1 .Lmy_do_w
	ds_read_b128 v[148:151], v200 offset:9216
	ds_read_b128 v[152:155], v201 offset:9216
	ds_read_b128 v[156:159], v200 offset:9248
	ds_read_b128 v[160:163], v201 offset:9248
	s_waitcnt lgkmcnt(2)
	v_mfma_f32_32x32x16_bf16 v[96:111], v[148:151], v[112:115], v[48:63]
	v_mfma_f32_32x32x16_bf16 v[80:95], v[152:155], v[112:115], v[48:63]
	s_waitcnt lgkmcnt(0)
	v_mfma_f32_32x32x16_bf16 v[96:111], v[156:159], v[116:119], v[96:111]
	v_mfma_f32_32x32x16_bf16 v[80:95], v[160:163], v[116:119], v[80:95]
	ds_read2_b64 v[164:167], v212 offset0:0 offset1:2
	ds_read2_b64 v[168:171], v213 offset0:32 offset1:34
	ds_read2_b64 v[172:175], v212 offset0:4 offset1:6
	ds_read2_b64 v[180:183], v213 offset0:36 offset1:38
	ds_read2_b64 v[184:187], v212 offset0:8 offset1:10
	ds_read2_b64 v[188:191], v213 offset0:40 offset1:42
	ds_read2_b64 v[192:195], v212 offset0:12 offset1:14
	ds_read2_b64 v[196:199], v213 offset0:44 offset1:46
	s_cmp_le_u32 s26, s25
	s_nop 1
	s_cbranch_scc1 .Lmy_d1_pv
	v_add_u32_e32 v1, s26, v131
	v_subrev_u32_e32 v2, 63, v1
	v_cmp_gt_u32_e32 vcc, v2, v138
	s_nop 1
	v_cndmask_b32_e32 v3, v96, v225, vcc
	v_cmp_lt_u32_e32 vcc, v2, v138
	v_subrev_u32_e32 v2, 61, v1
	s_nop 0
	v_cndmask_b32_e32 v96, v3, v96, vcc
	v_cndmask_b32_e32 v97, v225, v97, vcc
	v_cmp_le_u32_e32 vcc, v2, v138
	v_subrev_u32_e32 v2, 60, v1
	s_nop 0
	v_cndmask_b32_e32 v98, v225, v98, vcc
	v_cmp_le_u32_e32 vcc, v2, v138
	v_subrev_u32_e32 v2, 55, v1
	s_nop 0
	v_cndmask_b32_e32 v99, v225, v99, vcc
	v_cmp_le_u32_e32 vcc, v2, v138
	v_subrev_u32_e32 v2, 54, v1
	s_nop 0
	v_cndmask_b32_e32 v100, v225, v100, vcc
	v_cmp_le_u32_e32 vcc, v2, v138
	v_subrev_u32_e32 v2, 53, v1
	s_nop 0
	v_cndmask_b32_e32 v101, v225, v101, vcc
	v_cmp_le_u32_e32 vcc, v2, v138
	v_subrev_u32_e32 v2, 52, v1
	s_nop 0
	v_cndmask_b32_e32 v102, v225, v102, vcc
	v_cmp_le_u32_e32 vcc, v2, v138
	v_subrev_u32_e32 v2, 47, v1
	s_nop 0
	v_cndmask_b32_e32 v103, v225, v103, vcc
	v_cmp_le_u32_e32 vcc, v2, v138
	v_subrev_u32_e32 v2, 46, v1
	s_nop 0
	v_cndmask_b32_e32 v104, v225, v104, vcc
	v_cmp_le_u32_e32 vcc, v2, v138
	v_subrev_u32_e32 v2, 45, v1
	s_nop 0
	v_cndmask_b32_e32 v105, v225, v105, vcc
	v_cmp_le_u32_e32 vcc, v2, v138
	v_subrev_u32_e32 v2, 44, v1
	s_nop 0
	v_cndmask_b32_e32 v106, v225, v106, vcc
	v_cmp_le_u32_e32 vcc, v2, v138
	v_subrev_u32_e32 v2, 39, v1
	s_nop 0
	v_cndmask_b32_e32 v107, v225, v107, vcc
	v_cmp_le_u32_e32 vcc, v2, v138
	v_subrev_u32_e32 v2, 38, v1
	s_nop 0
	v_cndmask_b32_e32 v108, v225, v108, vcc
	v_cmp_le_u32_e32 vcc, v2, v138
	v_subrev_u32_e32 v2, 37, v1
	s_nop 0
	v_cndmask_b32_e32 v109, v225, v109, vcc
	v_cmp_le_u32_e32 vcc, v2, v138
	v_subrev_u32_e32 v2, 36, v1
	s_nop 0
	v_cndmask_b32_e32 v110, v225, v110, vcc
	v_cmp_le_u32_e32 vcc, v2, v138
	v_subrev_u32_e32 v2, 31, v1
	s_nop 0
	v_cndmask_b32_e32 v111, v225, v111, vcc
	v_cmp_le_u32_e32 vcc, v2, v138
	v_subrev_u32_e32 v2, 30, v1
	s_nop 0
	v_cndmask_b32_e32 v80, v225, v80, vcc
	v_cmp_le_u32_e32 vcc, v2, v138
	v_subrev_u32_e32 v2, 29, v1
	s_nop 0
	v_cndmask_b32_e32 v81, v225, v81, vcc
	v_cmp_le_u32_e32 vcc, v2, v138
	v_subrev_u32_e32 v2, 28, v1
	s_nop 0
	v_cndmask_b32_e32 v82, v225, v82, vcc
	v_cmp_le_u32_e32 vcc, v2, v138
	v_subrev_u32_e32 v2, 23, v1
	s_nop 0
	v_cndmask_b32_e32 v83, v225, v83, vcc
	v_cmp_le_u32_e32 vcc, v2, v138
	v_subrev_u32_e32 v2, 22, v1
	s_nop 0
	v_cndmask_b32_e32 v84, v225, v84, vcc
	v_cmp_le_u32_e32 vcc, v2, v138
	v_subrev_u32_e32 v2, 21, v1
	s_nop 0
	v_cndmask_b32_e32 v85, v225, v85, vcc
	v_cmp_le_u32_e32 vcc, v2, v138
	v_subrev_u32_e32 v2, 20, v1
	s_nop 0
	v_cndmask_b32_e32 v86, v225, v86, vcc
	v_cmp_le_u32_e32 vcc, v2, v138
	v_add_u32_e32 v2, -15, v1
	s_nop 0
	v_cndmask_b32_e32 v87, v225, v87, vcc
	v_cmp_le_u32_e32 vcc, v2, v138
	v_add_u32_e32 v2, -14, v1
	s_nop 0
	v_cndmask_b32_e32 v88, v225, v88, vcc
	v_cmp_le_u32_e32 vcc, v2, v138
	v_add_u32_e32 v2, -13, v1
	s_nop 0
	v_cndmask_b32_e32 v89, v225, v89, vcc
	v_cmp_le_u32_e32 vcc, v2, v138
	v_add_u32_e32 v2, -12, v1
	s_nop 0
	v_cndmask_b32_e32 v90, v225, v90, vcc
	v_cmp_le_u32_e32 vcc, v2, v138
	v_add_u32_e32 v2, -7, v1
	s_nop 0
	v_cndmask_b32_e32 v91, v225, v91, vcc
	v_cmp_le_u32_e32 vcc, v2, v138
	v_add_u32_e32 v2, -6, v1
	s_nop 0
	v_cndmask_b32_e32 v92, v225, v92, vcc
	v_cmp_le_u32_e32 vcc, v2, v138
	v_add_u32_e32 v2, -5, v1
	v_add_u32_e32 v1, -4, v1
	v_cndmask_b32_e32 v93, v225, v93, vcc
	v_cmp_le_u32_e32 vcc, v2, v138
	s_nop 1
	v_cndmask_b32_e32 v94, v225, v94, vcc
	v_cmp_le_u32_e32 vcc, v1, v138
	s_nop 1
	v_cndmask_b32_e32 v95, v225, v95, vcc

; #define LAS __attribute__((address_space(3)))
; __device__ __forceinline__ unsigned pk2(float lo, float hi) { f32x2_t v = {lo, hi}; bf16x2_t b = __builtin_convertvector(v, bf16x2_t); return __builtin_bit_cast(unsigned, b); }
; __device__ __forceinline__ int crow(int r, int hi) { return (r & 3) + 8 * (r >> 2) + 4 * hi; }
; template <bool DIFF>
; __device__ __forceinline__ void attn_unit(CA& A, int l, int b, int hh, int qb, LAS unsigned char* lds, float lam, float lam_init) {
;     ...
;         if (has_next) ATT_WRITE(buf ^ 1);
;         if (!DIFF) {
;             const int vote = (!first && !__any(nc_hi + qkb - m_ref + 2.0f * qkb >= -48.0f)) ? 1 : 0;
;             if (lane == 0) votes[(tt & 1) * 8 + wid] = vote;
;         }
;         __syncthreads();
;         if (!has_next) break;
;         if (!DIFF) {
;             const int pb_ = (tt & 1) * 8;
;             const int all = votes[pb_] & votes[pb_ + 1] & votes[pb_ + 2] & votes[pb_ + 3] & votes[pb_ + 4] & votes[pb_ + 5] & votes[pb_ + 6] & votes[pb_ + 7];
;             if (all) break;
;         }
;     }
;     ...
;     const float inv = 1.0f / ol[0];
;     const size_t orow = (size_t)b * SEQ + q0 + wq + r32;
;     if (!DIFF) {
; #pragma unroll
;         for (int dt = 0; dt < 2; ++dt)
; #pragma unroll
;             for (int g = 0; g < 4; ++g) {
;                 v2u w; w.x = pk2(o[dt][4 * g] * inv, o[dt][4 * g + 1] * inv); w.y = pk2(o[dt][4 * g + 2] * inv, o[dt][4 * g + 3] * inv);
;                 *(v2u*)(MIX + orow * DM + 768 + hh * 64 + 32 * dt + 8 * g + 4 * hi) = w;
;             }
;     } else {
;         LAS float* O2 = (LAS float*)(lds + AL_O2);
;         if (strm == 1) {
; #pragma unroll
;             for (int dt = 0; dt < 2; ++dt)
; #pragma unroll
;                 for (int r = 0; r < 16; ++r) O2[(wq + r32) * 65 + 32 * dt + crow(r, hi)] = o[dt][r] * inv;
;         }
.Lmy_do_w:
	s_andn2_b64 vcc, exec, s[4:5]
	s_cbranch_vccnz .Lmy_do_e
	s_waitcnt vmcnt(1)
	ds_write_b128 v139, v[120:123]
	s_waitcnt vmcnt(0)
	ds_write_b16 v140, v124 offset:18432
	ds_write_b16_d16_hi v140, v124 offset:18568
	ds_write_b16 v140, v125 offset:18704
	ds_write_b16_d16_hi v140, v125 offset:18840
	ds_write_b16 v140, v126 offset:18976
	ds_write_b16_d16_hi v140, v126 offset:19112
	ds_write_b16 v140, v127 offset:19248
	ds_write_b16_d16_hi v140, v127 offset:19384
.Lmy_do_e:
	s_add_i32 s26, s26, 64
	s_mov_b64 s[4:5], 0x50000
	v_lshl_add_u64 v[132:133], v[132:133], 0, s[4:5]
	s_cmp_lg_u32 s10, s11
	v_lshl_add_u64 v[134:135], v[134:135], 0, s[4:5]
	s_waitcnt lgkmcnt(0)
	s_barrier
	s_cbranch_scc0 .LBB0_751
	s_mov_b32 s31, s11
	s_branch .LBB0_741
.LBB0_751:
	s_nop 0
	v_div_scale_f32 v1, s[4:5], v64, v64, 1.0
	v_rcp_f32_e32 v2, v1
	v_div_scale_f32 v3, vcc, 1.0, v64, 1.0
	s_cmp_lg_u32 s24, 1
	v_fma_f32 v4, -v1, v2, 1.0
	v_fmac_f32_e32 v2, v4, v2
	v_mul_f32_e32 v4, v3, v2
	v_fma_f32 v5, -v1, v4, v3
	v_fmac_f32_e32 v4, v5, v2
	v_fma_f32 v1, -v1, v4, v3
	v_div_fmas_f32 v1, v1, v2, v4
	v_div_fixup_f32 v2, v1, v64, 1.0
	s_cbranch_scc1 .LBB0_753
	v_or_b32_e32 v1, s20, v137
	v_mul_u32_u24_e32 v1, 0x104, v1
	v_add3_u32 v1, 0, v1, v130
	v_add_u32_e32 v3, 0x9400, v1
	v_pk_mul_f32 v[4:5], v[32:33], v[2:3] op_sel_hi:[1,0]
	ds_write2_b32 v3, v4, v5 offset1:1
	v_add_u32_e32 v3, 0x9408, v1
	v_pk_mul_f32 v[4:5], v[34:35], v[2:3] op_sel_hi:[1,0]
	ds_write2_b32 v3, v4, v5 offset1:1
	v_add_u32_e32 v3, 0x9420, v1
	v_pk_mul_f32 v[4:5], v[36:37], v[2:3] op_sel_hi:[1,0]
	ds_write2_b32 v3, v4, v5 offset1:1
	v_add_u32_e32 v3, 0x9428, v1
	v_pk_mul_f32 v[4:5], v[38:39], v[2:3] op_sel_hi:[1,0]
	ds_write2_b32 v3, v4, v5 offset1:1
	v_add_u32_e32 v3, 0x9440, v1
	v_pk_mul_f32 v[4:5], v[40:41], v[2:3] op_sel_hi:[1,0]
	ds_write2_b32 v3, v4, v5 offset1:1
	v_add_u32_e32 v3, 0x9448, v1
	v_pk_mul_f32 v[4:5], v[42:43], v[2:3] op_sel_hi:[1,0]
	ds_write2_b32 v3, v4, v5 offset1:1
	v_add_u32_e32 v3, 0x9460, v1
	v_pk_mul_f32 v[4:5], v[44:45], v[2:3] op_sel_hi:[1,0]
	ds_write2_b32 v3, v4, v5 offset1:1
	v_add_u32_e32 v3, 0x9468, v1
	v_pk_mul_f32 v[4:5], v[46:47], v[2:3] op_sel_hi:[1,0]
	ds_write2_b32 v3, v4, v5 offset1:1
	v_add_u32_e32 v3, 0x9480, v1
	v_pk_mul_f32 v[4:5], v[16:17], v[2:3] op_sel_hi:[1,0]
	ds_write2_b32 v3, v4, v5 offset1:1
	v_add_u32_e32 v3, 0x9488, v1
	v_pk_mul_f32 v[4:5], v[18:19], v[2:3] op_sel_hi:[1,0]
	ds_write2_b32 v3, v4, v5 offset1:1
	v_add_u32_e32 v3, 0x94a0, v1
	v_pk_mul_f32 v[4:5], v[20:21], v[2:3] op_sel_hi:[1,0]
	ds_write2_b32 v3, v4, v5 offset1:1
	v_add_u32_e32 v3, 0x94a8, v1
	v_pk_mul_f32 v[4:5], v[22:23], v[2:3] op_sel_hi:[1,0]
	ds_write2_b32 v3, v4, v5 offset1:1
	v_add_u32_e32 v3, 0x94c0, v1
	v_pk_mul_f32 v[4:5], v[24:25], v[2:3] op_sel_hi:[1,0]
	ds_write2_b32 v3, v4, v5 offset1:1
	v_add_u32_e32 v3, 0x94c8, v1
	v_pk_mul_f32 v[4:5], v[26:27], v[2:3] op_sel_hi:[1,0]
	ds_write2_b32 v3, v4, v5 offset1:1
	v_add_u32_e32 v3, 0x94e0, v1
	v_pk_mul_f32 v[4:5], v[28:29], v[2:3] op_sel_hi:[1,0]
	ds_write2_b32 v3, v4, v5 offset1:1
	v_add_u32_e32 v1, 0x94e8, v1
	v_pk_mul_f32 v[4:5], v[30:31], v[2:3] op_sel_hi:[1,0]
	ds_write2_b32 v1, v4, v5 offset1:1
